# P1 peeled first K-iteration (C=0 first MFMAs, relaxed first waits) + P8 tail conversion shared with the six-unit workgroups after their last unit (split at item 0x6c00)
# speedup vs baseline: 1.0048x; 1.0022x over previous
.LBB0_803:
	s_cmpk_gt_i32 s2, 0x7f
	v_readlane_b32 s6, v252, 19
	s_mov_b64 s[4:5], -1
	v_readlane_b32 s7, v252, 20
	s_and_b64 s[4:5], s[6:7], s[4:5]
	s_andn2_b64 vcc, exec, s[4:5]
	s_cbranch_vccnz .LBB0_876
	v_readlane_b32 s4, v254, 20
	v_readlane_b32 s7, v254, 23
	v_readlane_b32 s14, v254, 24
	v_mov_b32_e32 v0, s4
	s_and_b64 s[4:5], s[0:1], exec
	v_readlane_b32 s4, v254, 21
	ds_read_b64 v[2:3], v0
	v_readlane_b32 s5, v254, 22
	v_mov_b32_e32 v0, s4
	ds_read_b64 v[6:7], v0
	v_mov_b32_e32 v0, s5
	s_waitcnt lgkmcnt(1)
	v_readfirstlane_b32 s12, v3
	v_readfirstlane_b32 s13, v2
	ds_read2_b64 v[2:5], v0 offset1:1
	v_mov_b32_e32 v0, s7
	s_waitcnt lgkmcnt(1)
	v_readfirstlane_b32 s5, v7
	v_readfirstlane_b32 s6, v6
	ds_read_b64 v[6:7], v0
	v_mov_b32_e32 v0, s14
	v_readlane_b32 s14, v254, 31
	s_waitcnt lgkmcnt(1)
	v_readfirstlane_b32 s7, v3
	v_readfirstlane_b32 s8, v2
	v_readfirstlane_b32 s9, v5
	v_readfirstlane_b32 s18, v4
	ds_read2_b64 v[2:5], v0 offset1:1
	v_mov_b32_e32 v0, s14
	s_waitcnt lgkmcnt(1)
	v_readfirstlane_b32 s28, v7
	v_readfirstlane_b32 s29, v6
	ds_read_b64 v[6:7], v0
	v_mov_b32_e32 v0, v1
	v_readlane_b32 s14, v252, 8
	v_mbcnt_lo_u32_b32 v0, -1, v0
	v_mbcnt_hi_u32_b32 v66, -1, v0
	s_movk_i32 s4, 0x7700
	s_movk_i32 s99, 0x6c00
	v_add_u32_e32 v0, s14, v66
	s_cselect_b32 s4, 0x5100, s4
	s_cselect_b32 s99, 0x5100, s99
	v_readfirstlane_b32 s14, v0
	s_ashr_i32 s40, s14, 6
	s_cmpk_gt_i32 s2, 0x7f
	s_cselect_b32 s4, s99, s4
	s_cselect_b32 s99, 0x4200, s99
	s_lshl_b32 s2, s2, 3
	s_add_i32 s2, s2, s40
	s_add_i32 s2, s2, s99
	s_waitcnt lgkmcnt(1)
	v_readfirstlane_b32 s35, v3
	v_readfirstlane_b32 s44, v2
	v_readfirstlane_b32 s45, v5
	v_readfirstlane_b32 s46, v4
	s_waitcnt lgkmcnt(0)
	v_readfirstlane_b32 s47, v7
	s_cmp_ge_i32 s2, s4
	v_readfirstlane_b32 s48, v6
	s_cbranch_scc1 .LBB0_876
	s_add_u32 s49, s13, 0x100000
	s_addc_u32 s50, s12, 0
	s_add_u32 s51, s13, 0x76e00000
	s_addc_u32 s52, s12, 0
	s_add_u32 s53, s13, 0x16500000
	s_addc_u32 s54, s12, 0
	s_add_u32 s55, s13, 0x18500000
	s_addc_u32 s60, s12, 0
	s_add_u32 s61, s13, 0x23500000
	s_addc_u32 s62, s12, 0
	s_mul_hi_i32 s12, s2, 0x1948b0fd
	s_lshr_b32 s13, s12, 31
	s_ashr_i32 s12, s12, 11
	s_add_i32 s12, s12, s13
	v_readlane_b32 s14, v254, 36
	s_add_i32 s20, s12, s14
	s_mulk_i32 s12, 0x5100
	s_sub_i32 s41, s2, s12
	v_readlane_b32 s15, v254, 37
	s_cmpk_gt_i32 s41, 0x1dff
	s_mov_b64 s[38:39], -1
	s_cbranch_scc0 .LBB0_833
	s_ashr_i32 s21, s20, 31
	s_cmpk_gt_u32 s41, 0x25ff
	s_cbranch_scc0 .LBB0_830
	s_cmpk_gt_u32 s41, 0x27ff
	s_cbranch_scc0 .LBB0_827
	s_cmpk_gt_u32 s41, 0x2bff
	s_cbranch_scc0 .LBB0_824
	s_cmpk_gt_u32 s41, 0x2fff
	s_cbranch_scc0 .LBB0_821
	s_cmpk_gt_u32 s41, 0x3aff
	s_mul_hi_i32 s30, s20, 0x2c00000
	s_mul_i32 s31, s20, 0x2c00000
	s_cbranch_scc0 .LBB0_818
	s_mov_b64 s[22:23], -1
	s_cmpk_gt_u32 s41, 0x45ff
	s_mov_b64 s[14:15], -1
	s_cbranch_scc0 .LBB0_813
	s_add_i32 s42, s41, 0xffffba00
	s_add_u32 s16, s48, s31
	s_addc_u32 s17, s47, s30
	s_mul_i32 s12, s20, 0x1600000
	s_mul_hi_i32 s13, s20, 0x1600000
	s_add_u32 s12, s61, s12
	s_addc_u32 s13, s62, s13
	s_mov_b64 s[14:15], 0
